# P5/P6/P7 hand-off counter waits poll at s_sleep 2 instead of s_sleep 8 (shorter detection latency per hop)
# baseline (speedup 1.0000x reference)
.LBB0_1055:
	global_load_dword v3, v2, s[20:21] sc1
	s_mov_b64 s[22:23], -1
	s_waitcnt vmcnt(0)
	v_readfirstlane_b32 s5, v3
	s_cmp_ge_u32 s5, s33
	s_cbranch_scc1 .LBB0_1054
	s_sleep 2
	global_load_dword v3, v2, s[20:21] sc1
	s_waitcnt vmcnt(0)
	v_readfirstlane_b32 s5, v3
	s_cmp_lt_u32 s5, s33
	s_cbranch_scc0 .LBB0_1054
	s_sleep 2
	global_load_dword v3, v2, s[20:21] sc1
	s_waitcnt vmcnt(0)
	v_readfirstlane_b32 s5, v3
	s_cmp_lt_u32 s5, s33
	s_cbranch_scc0 .LBB0_1054
	s_sleep 2
	global_load_dword v3, v2, s[20:21] sc1
	s_waitcnt vmcnt(0)
	v_readfirstlane_b32 s5, v3
	s_cmp_lt_u32 s5, s33
	s_cbranch_scc0 .LBB0_1054
	s_sleep 2
	global_load_dword v3, v2, s[20:21] sc1
	s_waitcnt vmcnt(0)
	v_readfirstlane_b32 s5, v3
	s_cmp_lt_u32 s5, s33
	s_cbranch_scc0 .LBB0_1054
	s_add_i32 s4, s4, -5
	s_cmp_eq_u32 s4, 0
	s_cselect_b64 s[22:23], -1, 0
	s_sleep 2
	s_branch .LBB0_1054

.LBB0_1070:
	global_load_dword v3, v2, s[0:1] sc1
	s_mov_b64 s[18:19], -1
	s_waitcnt vmcnt(0)
	v_readfirstlane_b32 s5, v3
	s_cmp_ge_u32 s5, s94
	s_cbranch_scc1 .LBB0_1069
	s_sleep 2
	global_load_dword v3, v2, s[0:1] sc1
	s_waitcnt vmcnt(0)
	v_readfirstlane_b32 s5, v3
	s_cmp_lt_u32 s5, s94
	s_cbranch_scc0 .LBB0_1069
	s_sleep 2
	global_load_dword v3, v2, s[0:1] sc1
	s_waitcnt vmcnt(0)
	v_readfirstlane_b32 s5, v3
	s_cmp_lt_u32 s5, s94
	s_cbranch_scc0 .LBB0_1069
	s_sleep 2
	global_load_dword v3, v2, s[0:1] sc1
	s_waitcnt vmcnt(0)
	v_readfirstlane_b32 s5, v3
	s_cmp_lt_u32 s5, s94
	s_cbranch_scc0 .LBB0_1069
	s_sleep 2
	global_load_dword v3, v2, s[0:1] sc1
	s_waitcnt vmcnt(0)
	v_readfirstlane_b32 s5, v3
	s_cmp_lt_u32 s5, s94
	s_cbranch_scc0 .LBB0_1069
	s_add_i32 s4, s4, -5
	s_cmp_eq_u32 s4, 0
	s_cselect_b64 s[18:19], -1, 0
	s_sleep 2
	s_branch .LBB0_1069

.LBB0_1273:
	global_load_dword v3, v2, s[0:1] sc1
	s_mov_b64 s[18:19], -1
	s_waitcnt vmcnt(0)
	v_readfirstlane_b32 s5, v3
	s_cmp_ge_u32 s5, s36
	s_cbranch_scc1 .LBB0_1272
	s_sleep 2
	global_load_dword v3, v2, s[0:1] sc1
	s_waitcnt vmcnt(0)
	v_readfirstlane_b32 s5, v3
	s_cmp_lt_u32 s5, s36
	s_cbranch_scc0 .LBB0_1272
	s_sleep 2
	global_load_dword v3, v2, s[0:1] sc1
	s_waitcnt vmcnt(0)
	v_readfirstlane_b32 s5, v3
	s_cmp_lt_u32 s5, s36
	s_cbranch_scc0 .LBB0_1272
	s_sleep 2
	global_load_dword v3, v2, s[0:1] sc1
	s_waitcnt vmcnt(0)
	v_readfirstlane_b32 s5, v3
	s_cmp_lt_u32 s5, s36
	s_cbranch_scc0 .LBB0_1272
	s_sleep 2
	global_load_dword v3, v2, s[0:1] sc1
	s_waitcnt vmcnt(0)
	v_readfirstlane_b32 s5, v3
	s_cmp_lt_u32 s5, s36
	s_cbranch_scc0 .LBB0_1272
	s_add_i32 s4, s4, -5
	s_cmp_eq_u32 s4, 0
	s_cselect_b64 s[18:19], -1, 0
	s_sleep 2
	s_branch .LBB0_1272

.LBB0_1356:
	global_load_dword v3, v2, s[0:1] sc1
	s_mov_b64 s[18:19], -1
	s_waitcnt vmcnt(0)
	v_readfirstlane_b32 s9, v3
	s_cmp_ge_u32 s9, s94
	s_cbranch_scc1 .LBB0_1355
	s_sleep 2
	global_load_dword v3, v2, s[0:1] sc1
	s_waitcnt vmcnt(0)
	v_readfirstlane_b32 s9, v3
	s_cmp_lt_u32 s9, s94
	s_cbranch_scc0 .LBB0_1355
	s_sleep 2
	global_load_dword v3, v2, s[0:1] sc1
	s_waitcnt vmcnt(0)
	v_readfirstlane_b32 s9, v3
	s_cmp_lt_u32 s9, s94
	s_cbranch_scc0 .LBB0_1355
	s_sleep 2
	global_load_dword v3, v2, s[0:1] sc1
	s_waitcnt vmcnt(0)
	v_readfirstlane_b32 s9, v3
	s_cmp_lt_u32 s9, s94
	s_cbranch_scc0 .LBB0_1355
	s_sleep 2
	global_load_dword v3, v2, s[0:1] sc1
	s_waitcnt vmcnt(0)
	v_readfirstlane_b32 s9, v3
	s_cmp_lt_u32 s9, s94
	s_cbranch_scc0 .LBB0_1355
	s_add_i32 s6, s6, -5
	s_cmp_eq_u32 s6, 0
	s_cselect_b64 s[18:19], -1, 0
	s_sleep 2
	s_branch .LBB0_1355

.LBB0_1531:
	global_load_dword v2, v3, s[22:23] sc1
	s_waitcnt vmcnt(0)
	v_readfirstlane_b32 s0, v2
	s_cmp_ge_u32 s0, s94
	s_mov_b64 s[0:1], -1
	s_cbranch_scc1 .LBB0_1530
	s_sleep 2
	global_load_dword v2, v3, s[22:23] sc1
	s_waitcnt vmcnt(0)
	v_readfirstlane_b32 s0, v2
	s_cmp_lt_u32 s0, s94
	s_mov_b64 s[0:1], -1
	s_cbranch_scc0 .LBB0_1530
	s_sleep 2
	global_load_dword v2, v3, s[22:23] sc1
	s_waitcnt vmcnt(0)
	v_readfirstlane_b32 s0, v2
	s_cmp_lt_u32 s0, s94
	s_mov_b64 s[0:1], -1
	s_cbranch_scc0 .LBB0_1530
	s_sleep 2
	global_load_dword v2, v3, s[22:23] sc1
	s_waitcnt vmcnt(0)
	v_readfirstlane_b32 s0, v2
	s_cmp_lt_u32 s0, s94
	s_mov_b64 s[0:1], -1
	s_cbranch_scc0 .LBB0_1530
	s_sleep 2
	global_load_dword v2, v3, s[22:23] sc1
	s_waitcnt vmcnt(0)
	v_readfirstlane_b32 s0, v2
	s_cmp_lt_u32 s0, s94
	s_mov_b64 s[0:1], -1
	s_cbranch_scc0 .LBB0_1530
	s_add_i32 s4, s4, -5
	s_cmp_eq_u32 s4, 0
	s_cselect_b64 s[0:1], -1, 0
	s_sleep 2
	s_branch .LBB0_1530
